# v67 + code placement: one s_nop 0 at kernel entry (every later instruction shifted by 4 bytes; docs 9.3 placement rule)
# baseline (speedup 1.0000x reference)
_ZN2fk3fwdENS_4ArgsE:
	s_nop 0
	s_mov_b32 s94, s2
	s_load_dwordx8 s[52:59], s[0:1], 0x80
	s_add_u32 s2, s0, 0xa0
	s_addc_u32 s3, s1, 0
	v_readfirstlane_b32 s8, v0
	v_writelane_b32 v249, s2, 0
	s_nop 1
	v_writelane_b32 v249, s3, 1
	s_movk_i32 s2, 0x80
	v_cmp_gt_u32_e32 vcc, s2, v0
	s_and_saveexec_b64 s[4:5], vcc
	v_lshl_add_u32 v1, v0, 2, 0
	v_add_u32_e32 v1, 0x27e00, v1
	v_mov_b32_e32 v2, 0
	ds_write_b32 v1, v2
	s_or_b64 exec, exec, s[4:5]
	s_load_dword s2, s[0:1], 0xa0
	s_load_dwordx16 s[64:79], s[0:1], 0x40
	s_waitcnt lgkmcnt(0)
	s_barrier
	v_writelane_b32 v249, s2, 2
	s_nop 1
	v_writelane_b32 v249, s3, 3
	s_getreg_b32 s2, hwreg(HW_REG_XCC_ID, 0, 4)
	s_and_b32 s2, s2, 15
	v_writelane_b32 v249, s2, 4
	v_cmp_eq_u32_e64 s[2:3], 0, v0
	s_mov_b64 s[4:5], exec
	s_nop 0
	v_writelane_b32 v249, s2, 5
	s_nop 1
	v_writelane_b32 v249, s3, 6
	s_and_b64 s[2:3], s[4:5], s[2:3]
	s_mov_b64 exec, s[2:3]
	s_cbranch_execz .LBB0_5
	s_mov_b64 s[6:7], exec
	v_mbcnt_lo_u32_b32 v1, s6, 0
	v_mbcnt_hi_u32_b32 v1, s7, v1
	v_cmp_eq_u32_e32 vcc, 0, v1
	s_and_b64 s[2:3], exec, vcc
	s_mov_b64 exec, s[2:3]
	s_cbranch_execz .LBB0_5
	v_readlane_b32 s2, v249, 4
	s_lshl_b32 s2, s2, 8
	s_bcnt1_i32_b64 s3, s[6:7]
	v_mov_b32_e32 v1, s2
	v_mov_b32_e32 v2, s3
	global_atomic_add v1, v2, s[56:57] offset:1024
